# v6 + static priority variant lo (waves 0-3 raised / no priority at all), per-block flips removed
# baseline (speedup 1.0000x reference)
; #define PG8_STAGE(bufoff, gbase, voff) do { _Pragma("unroll") for (int _i = 0; _i < 2; ++_i) \
;         __builtin_amdgcn_global_load_lds((const unsigned*)((const char*)(gbase) + (voff)[_i]), (LAS unsigned*)(lds + (bufoff) + ldsw + _i * 8192), 16, 0, 0); } while (0)
; #define PG8_WAIT_V(n) asm volatile("s_waitcnt vmcnt(" #n ")" ::: "memory")
; #define PG8_BAR __builtin_amdgcn_s_barrier()
; template <class Epi, class Ptrs>
; __device__ __forceinline__ void gemm_phase(LAS unsigned char* lds, const int K, const StaticOrder& S, const Ptrs& P, const Epi& E) {
;     ...
;     for (int i = 0; i < 2; ++i) { int R, C; stage_rc(tid * 16 + i * 8192, R, C); const int Rb = (R & ~31) + perm32(R & 31);
;         voffA[i] = (unsigned)(R * K + C) * 2u; voffB[i] = (unsigned)(Rb * K + C) * 2u; }
;     const size_t kstep = (size_t)(BK * 2);
;     const size_t hstep = (size_t)HALF * K * 2;
;     const unsigned ldsw = (unsigned)wid * 1024u;
;     const int aoff = lds_byte(wr * 64 + fr, fq * 8), boff = lds_byte(wc * 32 + fr, fq * 8);
;     ...
;     Unit cur, nxt; int ui = 0;
;     if (!S.next(0, cur)) return;
;     f32x4 acc[2][2][4][2];
; #pragma unroll
;     for (int a = 0; a < 2; ++a)
; #pragma unroll
;         for (int b = 0; b < 2; ++b)
; #pragma unroll
;             for (int m = 0; m < 4; ++m)
; #pragma unroll
;                 for (int n = 0; n < 2; ++n) acc[a][b][m][n] = (f32x4){0.f, 0.f, 0.f, 0.f};
;     bf16x8 At[4][2], B0[2][2], B1[2][2];
;     const char* cA; const char* cB; P.get(cur, cA, cB);
;     PG8_STAGE(PG8_SB(0, 0), cB, voffB); PG8_STAGE(PG8_SA(0, 0), cA, voffA); PG8_STAGE(PG8_SB(0, 1), cB + hstep, voffB); PG8_STAGE(PG8_SA(0, 1), cA + hstep, voffA);
;     if (wr == 1) PG8_BAR;
;     PG8_WAIT_V(4); PG8_BAR;
;     PG8_STAGE(PG8_SB(1, 0), cB + kstep, voffB); PG8_STAGE(PG8_SA(1, 0), cA + kstep, voffA); PG8_STAGE(PG8_SB(1, 1), cB + hstep + kstep, voffB);
;     PG8_WAIT_V(6); PG8_BAR;
.LBB0_120:
	s_add_u32 s4, s28, 0x35000000
	s_addc_u32 s5, s29, 0
	s_mov_b64 s[58:59], 0x80
	v_writelane_b32 v254, s4, 0
	v_lshl_add_u64 v[6:7], v[6:7], 0, s[58:59]
	s_waitcnt vmcnt(4)
	s_barrier
	v_writelane_b32 v254, s5, 1
	s_add_u32 s4, s28, 0x26000000
	s_addc_u32 s5, s29, 0
	s_add_u32 s42, s28, 0x32000000
	s_addc_u32 s43, s29, 0
	s_add_u32 s44, s28, 0x2000000
	s_addc_u32 s45, s29, 0
	s_add_u32 s48, s26, 0xc000000
	s_addc_u32 s49, s27, 0
	s_add_u32 s54, s28, 0x3e000000
	s_addc_u32 s55, s29, 0
	s_add_u32 s56, s28, 0xe000000
	s_addc_u32 s57, s29, 0
	s_lshl_b32 s1, s1, 5
	s_and_b32 s88, s1, 0x60
	s_add_i32 m0, s67, 0x18000
	v_writelane_b32 v254, s4, 2
	s_ashr_i32 s86, s3, 31
	s_ashr_i32 s87, s2, 31
	s_lshl_b32 s20, s0, 13
	s_lshl_b32 s1, s88, 7
	global_load_lds_dwordx4 v[6:7], off
	v_lshl_add_u64 v[4:5], v[4:5], 0, s[58:59]
	s_add_i32 m0, s67, 0x1a000
	s_add_i32 s89, s67, 0x8000
	s_add_i32 s90, s67, 0xa000
	v_writelane_b32 v254, s5, 3
	global_load_lds_dwordx4 v[4:5], off
	v_lshl_add_u64 v[2:3], v[2:3], 0, s[58:59]
	s_mov_b32 m0, s89
	s_add_u32 s4, s78, 0x40080
	global_load_lds_dwordx4 v[2:3], off
	v_lshl_add_u64 v[0:1], v[0:1], 0, s[58:59]
	s_mov_b32 m0, s90
	s_addc_u32 s5, s79, 0
	global_load_lds_dwordx4 v[0:1], off
	s_add_i32 m0, s67, 0x1c000
	v_lshl_add_u64 v[0:1], s[4:5], 0, v[134:135]
	global_load_lds_dwordx4 v[0:1], off
	v_lshl_add_u64 v[0:1], s[4:5], 0, v[138:139]
	s_add_i32 m0, s67, 0x1e000
	v_lshlrev_b32_e32 v2, 6, v208
	global_load_lds_dwordx4 v[0:1], off
	v_and_b32_e32 v0, 15, v208
	v_lshlrev_b32_e32 v1, 1, v130
	s_movk_i32 s4, 0x3c0
	v_lshlrev_b32_e32 v3, 2, v208
	v_and_or_b32 v2, v2, s4, v1
	v_and_b32_e32 v3, 32, v3
	v_cmp_eq_u32_e64 s[10:11], 0, v0
	v_lshl_or_b32 v129, s0, 6, v0
	v_lshl_or_b32 v0, v0, 6, v1
	v_lshlrev_b32_e32 v1, 8, v208
	v_bitop3_b32 v131, s1, v2, v3 bitop3:0xf6
	v_and_b32_e32 v1, 0x38000, v1
	v_lshlrev_b32_e32 v2, 11, v10
	v_or3_b32 v1, v8, v1, v2
	v_add_u32_e32 v142, v1, v9
	v_lshlrev_b32_e32 v1, 4, v11
	s_waitcnt vmcnt(6)
	v_and_b32_e32 v1, 0x78000, v1
	v_bitop3_b32 v0, v0, s20, v3 bitop3:0xde
	v_or3_b32 v1, v8, v1, v2
	s_add_i32 s91, 0, 0x10000
	s_add_i32 s92, 0, 0x14000
	v_or_b32_e32 v204, s88, v130
	v_mov_b32_e32 v143, v141
	v_add_u32_e32 v144, v1, v9
	v_mov_b32_e32 v145, v141
	v_mov_b64_e32 v[146:147], 0x2100
	v_mov_b64_e32 v[148:149], 0x20ff
	v_add_u32_e32 v205, s91, v131
	v_add_u32_e32 v206, 0, v0
	v_add_u32_e32 v207, s92, v131
	s_mov_b32 s60, 0xbfb8aa3b
	s_lshl_b32 s62, s0, 2
	s_mov_b32 s64, 0x3dd2d3e7
	s_mov_b32 s66, 0xc0135761
	s_mov_b32 s93, 0x600000
	s_mov_b32 s94, 0x900000
	s_mov_b32 s95, 0x1800000
	s_mov_b32 s96, 0x1b00000
	s_mov_b32 s97, 0x1e00000
	s_mov_b32 s98, 0x2100000
	s_mov_b32 s99, 0x40000
	s_mov_b32 s22, 0x48000
	s_mov_b32 s23, 0x50000
	s_mov_b32 s24, 0
	s_cmpk_gt_u32 s61, 0xff
	s_cbranch_scc1 .Lsprio_0
	s_setprio 1

; #define PG8_STAGE(bufoff, gbase, voff) do { _Pragma("unroll") for (int _i = 0; _i < 2; ++_i) \
;         __builtin_amdgcn_global_load_lds((const unsigned*)((const char*)(gbase) + (voff)[_i]), (LAS unsigned*)(lds + (bufoff) + ldsw + _i * 8192), 16, 0, 0); } while (0)
; #define PG8_WAIT_V(n) asm volatile("s_waitcnt vmcnt(" #n ")" ::: "memory")
; #define PG8_BAR __builtin_amdgcn_s_barrier()
; template <class Epi, class Ptrs>
; __device__ __forceinline__ void gemm_phase(LAS unsigned char* lds, const int K, const StaticOrder& S, const Ptrs& P, const Epi& E) {
;     ...
;     for (int i = 0; i < 2; ++i) { int R, C; stage_rc(tid * 16 + i * 8192, R, C); const int Rb = (R & ~31) + perm32(R & 31);
;         voffA[i] = (unsigned)(R * K + C) * 2u; voffB[i] = (unsigned)(Rb * K + C) * 2u; }
;     const size_t kstep = (size_t)(BK * 2);
;     const size_t hstep = (size_t)HALF * K * 2;
;     const unsigned ldsw = (unsigned)wid * 1024u;
;     const int aoff = lds_byte(wr * 64 + fr, fq * 8), boff = lds_byte(wc * 32 + fr, fq * 8);
;     ...
;     Unit cur, nxt; int ui = 0;
;     if (!S.next(0, cur)) return;
;     f32x4 acc[2][2][4][2];
; #pragma unroll
;     for (int a = 0; a < 2; ++a)
; #pragma unroll
;         for (int b = 0; b < 2; ++b)
; #pragma unroll
;             for (int m = 0; m < 4; ++m)
; #pragma unroll
;                 for (int n = 0; n < 2; ++n) acc[a][b][m][n] = (f32x4){0.f, 0.f, 0.f, 0.f};
;     bf16x8 At[4][2], B0[2][2], B1[2][2];
;     const char* cA; const char* cB; P.get(cur, cA, cB);
;     PG8_STAGE(PG8_SB(0, 0), cB, voffB); PG8_STAGE(PG8_SA(0, 0), cA, voffA); PG8_STAGE(PG8_SB(0, 1), cB + hstep, voffB); PG8_STAGE(PG8_SA(0, 1), cA + hstep, voffA);
;     if (wr == 1) PG8_BAR;
;     PG8_WAIT_V(4); PG8_BAR;
;     PG8_STAGE(PG8_SB(1, 0), cB + kstep, voffB); PG8_STAGE(PG8_SA(1, 0), cA + kstep, voffA); PG8_STAGE(PG8_SB(1, 1), cB + hstep + kstep, voffB);
;     PG8_WAIT_V(6); PG8_BAR;
.LBB0_346:
	s_add_u32 s14, s28, 0x2000000
	s_addc_u32 s15, s29, 0
	s_add_u32 s16, s28, 0x3e000000
	s_addc_u32 s17, s29, 0
	s_ashr_i32 s58, s3, 31
	s_ashr_i32 s59, s2, 31
	s_add_u32 s60, s38, 0xf8000000
	s_mov_b64 s[18:19], 0x80
	s_addc_u32 s61, s39, -1
	s_and_b32 s62, s1, 3
	s_add_i32 m0, s54, 0x18000
	v_lshl_add_u64 v[6:7], v[6:7], 0, s[18:19]
	s_lshl_b32 s1, s0, 13
	s_lshl_b32 s20, s62, 12
	s_waitcnt vmcnt(4)
	s_barrier
	global_load_lds_dwordx4 v[6:7], off
	v_lshl_add_u64 v[4:5], v[4:5], 0, s[18:19]
	s_add_i32 m0, s54, 0x1a000
	s_add_i32 s63, s54, 0x8000
	s_add_i32 s64, s54, 0xa000
	global_load_lds_dwordx4 v[4:5], off
	v_lshl_add_u64 v[2:3], v[2:3], 0, s[18:19]
	s_mov_b32 m0, s63
	s_add_u32 s4, s42, 0x40080
	global_load_lds_dwordx4 v[2:3], off
	v_lshl_add_u64 v[0:1], v[0:1], 0, s[18:19]
	s_mov_b32 m0, s64
	s_addc_u32 s5, s43, 0
	global_load_lds_dwordx4 v[0:1], off
	s_add_i32 m0, s54, 0x1c000
	v_lshl_add_u64 v[0:1], s[4:5], 0, v[178:179]
	global_load_lds_dwordx4 v[0:1], off
	v_lshl_add_u64 v[0:1], s[4:5], 0, v[182:183]
	s_add_i32 m0, s54, 0x1e000
	v_lshlrev_b32_e32 v4, 6, v208
	global_load_lds_dwordx4 v[0:1], off
	v_bfe_u32 v1, v208, 4, 2
	v_lshlrev_b32_e32 v2, 3, v1
	v_lshlrev_b32_e32 v3, 4, v1
	v_cmp_eq_u32_e64 s[6:7], 0, v1
	v_lshlrev_b32_e32 v1, 8, v208
	v_lshl_or_b32 v206, s62, 5, v2
	v_and_b32_e32 v1, 0x38000, v1
	v_lshlrev_b32_e32 v2, 11, v10
	v_or3_b32 v1, v8, v1, v2
	v_and_b32_e32 v0, 15, v208
	s_movk_i32 s4, 0x3c0
	v_lshlrev_b32_e32 v5, 2, v208
	v_add_u32_e32 v184, v1, v9
	v_lshlrev_b32_e32 v1, 4, v11
	v_and_or_b32 v4, v4, s4, v3
	v_and_b32_e32 v5, 32, v5
	v_lshl_or_b32 v204, s0, 6, v0
	v_lshl_or_b32 v0, v0, 6, v3
	s_waitcnt vmcnt(6)
	v_and_b32_e32 v1, 0x78000, v1
	v_bitop3_b32 v0, v0, s1, v5 bitop3:0xde
	v_bitop3_b32 v205, s20, v4, v5 bitop3:0xf6
	v_or3_b32 v1, v8, v1, v2
	s_add_i32 s66, 0, 0x10000
	s_add_i32 s67, 0, 0x14000
	v_mov_b32_e32 v185, v179
	v_add_u32_e32 v186, v1, v9
	v_mov_b32_e32 v187, v179
	v_mov_b64_e32 v[188:189], 0x600
	v_mov_b64_e32 v[190:191], 0x5ff
	s_movk_i32 s65, 0xc1
	v_add_u32_e32 v207, s66, v205
	v_add_u32_e32 v209, 0, v0
	v_add_u32_e32 v210, s67, v205
	s_mov_b32 s68, 0
	s_cmpk_gt_u32 s46, 0xff
	s_cbranch_scc1 .Lsprio_1
	s_setprio 1

; #define PG8_STAGE(bufoff, gbase, voff) do { _Pragma("unroll") for (int _i = 0; _i < 2; ++_i) \
;         __builtin_amdgcn_global_load_lds((const unsigned*)((const char*)(gbase) + (voff)[_i]), (LAS unsigned*)(lds + (bufoff) + ldsw + _i * 8192), 16, 0, 0); } while (0)
; #define PG8_WAIT_V(n) asm volatile("s_waitcnt vmcnt(" #n ")" ::: "memory")
; #define PG8_BAR __builtin_amdgcn_s_barrier()
; template <class Epi, class Ptrs>
; __device__ __forceinline__ void gemm_phase(LAS unsigned char* lds, const int K, const StaticOrder& S, const Ptrs& P, const Epi& E) {
;     ...
;     for (int i = 0; i < 2; ++i) { int R, C; stage_rc(tid * 16 + i * 8192, R, C); const int Rb = (R & ~31) + perm32(R & 31);
;         voffA[i] = (unsigned)(R * K + C) * 2u; voffB[i] = (unsigned)(Rb * K + C) * 2u; }
;     const size_t kstep = (size_t)(BK * 2);
;     const size_t hstep = (size_t)HALF * K * 2;
;     const unsigned ldsw = (unsigned)wid * 1024u;
;     const int aoff = lds_byte(wr * 64 + fr, fq * 8), boff = lds_byte(wc * 32 + fr, fq * 8);
;     ...
;     Unit cur, nxt; int ui = 0;
;     if (!S.next(0, cur)) return;
;     f32x4 acc[2][2][4][2];
; #pragma unroll
;     for (int a = 0; a < 2; ++a)
; #pragma unroll
;         for (int b = 0; b < 2; ++b)
; #pragma unroll
;             for (int m = 0; m < 4; ++m)
; #pragma unroll
;                 for (int n = 0; n < 2; ++n) acc[a][b][m][n] = (f32x4){0.f, 0.f, 0.f, 0.f};
;     bf16x8 At[4][2], B0[2][2], B1[2][2];
;     const char* cA; const char* cB; P.get(cur, cA, cB);
;     PG8_STAGE(PG8_SB(0, 0), cB, voffB); PG8_STAGE(PG8_SA(0, 0), cA, voffA); PG8_STAGE(PG8_SB(0, 1), cB + hstep, voffB); PG8_STAGE(PG8_SA(0, 1), cA + hstep, voffA);
;     if (wr == 1) PG8_BAR;
;     PG8_WAIT_V(4); PG8_BAR;
;     PG8_STAGE(PG8_SB(1, 0), cB + kstep, voffB); PG8_STAGE(PG8_SA(1, 0), cA + kstep, voffA); PG8_STAGE(PG8_SB(1, 1), cB + hstep + kstep, voffB);
;     PG8_WAIT_V(6); PG8_BAR;
.LBB0_427:
	s_nop 0
	s_nop 0
	s_nop 0
	s_nop 0
	s_nop 0
	s_nop 0
	s_nop 0
	s_nop 0
	s_nop 0
	s_nop 0
	s_nop 0
	s_nop 0
	s_nop 0
	s_nop 0
	s_nop 0
	s_nop 0
	s_nop 0
	s_nop 0
	s_nop 0
	s_nop 0
	s_nop 0
	s_nop 0
	s_nop 0
	s_nop 0
	s_nop 0
	s_nop 0
	s_nop 0
	s_nop 0
	s_nop 0
	s_nop 0
	s_nop 0
	s_nop 0
	s_nop 0
	s_nop 0
	s_nop 0
	s_nop 0
	s_nop 0
	s_nop 0
	s_nop 0
	s_nop 0
	s_nop 0
	s_nop 0
	s_nop 0
	s_nop 0
	s_nop 0
	s_nop 0
	s_nop 0
	s_nop 0
	s_nop 0
	s_nop 0
	s_nop 0
	s_nop 0
	s_nop 0
	s_add_u32 s10, s28, 0xe000000
	s_addc_u32 s11, s29, 0
	s_lshl_b32 s4, s4, 5
	s_mov_b64 s[12:13], 0x80
	s_and_b32 s15, s4, 0x60
	s_add_i32 m0, s39, 0x18000
	v_lshl_add_u64 v[6:7], v[6:7], 0, s[12:13]
	s_ashr_i32 s60, s3, 31
	s_lshl_b32 s14, s1, 13
	s_lshl_b32 s16, s15, 7
	s_waitcnt vmcnt(4)
	s_barrier
	global_load_lds_dwordx4 v[6:7], off
	v_lshl_add_u64 v[4:5], v[4:5], 0, s[12:13]
	s_add_i32 m0, s39, 0x1a000
	s_add_i32 s61, s39, 0x8000
	s_add_i32 s62, s39, 0xa000
	global_load_lds_dwordx4 v[4:5], off
	v_lshl_add_u64 v[2:3], v[2:3], 0, s[12:13]
	s_mov_b32 m0, s61
	s_add_u32 s4, s42, 0x40080
	global_load_lds_dwordx4 v[2:3], off
	v_lshl_add_u64 v[0:1], v[0:1], 0, s[12:13]
	s_mov_b32 m0, s62
	s_addc_u32 s5, s43, 0
	global_load_lds_dwordx4 v[0:1], off
	s_add_i32 m0, s39, 0x1c000
	v_lshl_add_u64 v[0:1], s[4:5], 0, v[130:131]
	global_load_lds_dwordx4 v[0:1], off
	v_lshl_add_u64 v[0:1], s[4:5], 0, v[134:135]
	s_add_i32 m0, s39, 0x1e000
	s_sext_i32_i8 s69, s0
	global_load_lds_dwordx4 v[0:1], off
	v_and_b32_e32 v0, 15, v208
	v_lshlrev_b32_e32 v1, 1, v11
	v_lshlrev_b32_e32 v2, 6, v208
	s_movk_i32 s0, 0x3c0
	v_lshlrev_b32_e32 v3, 2, v208
	v_and_or_b32 v2, v2, s0, v1
	v_and_b32_e32 v3, 32, v3
	v_lshl_or_b32 v146, s1, 6, v0
	v_lshl_or_b32 v0, v0, 6, v1
	v_lshlrev_b32_e32 v1, 8, v208
	v_bitop3_b32 v147, s16, v2, v3 bitop3:0xf6
	v_and_b32_e32 v1, 0x38000, v1
	v_lshlrev_b32_e32 v2, 11, v10
	v_or3_b32 v1, v8, v1, v2
	v_add_u32_e32 v136, v1, v9
	v_lshlrev_b32_e32 v1, 4, v12
	s_waitcnt vmcnt(6)
	v_and_b32_e32 v1, 0x78000, v1
	v_bitop3_b32 v0, v0, s14, v3 bitop3:0xde
	v_or3_b32 v1, v8, v1, v2
	s_add_i32 s63, 0, 0x10000
	s_add_i32 s64, 0, 0x14000
	v_or_b32_e32 v148, s15, v11
	v_mov_b32_e32 v137, v131
	v_add_u32_e32 v138, v1, v9
	v_mov_b32_e32 v139, v131
	v_mov_b64_e32 v[140:141], 0x1800
	v_mov_b64_e32 v[142:143], 0x17ff
	v_add_u32_e32 v149, s63, v147
	v_add_u32_e32 v150, 0, v0
	v_add_u32_e32 v151, s64, v147
	s_mov_b64 s[14:15], 0x100000
	s_mov_b32 s65, 0x100000
	s_mov_b64 s[16:17], 0x120000
	s_mov_b32 s66, 0x120000
	s_mov_b64 s[18:19], 0x140000
	s_mov_b32 s67, 0x140000
	s_mov_b64 s[20:21], 0x160000
	s_mov_b32 s68, 0x160000
	s_cmpk_gt_u32 s46, 0xff
	s_cbranch_scc1 .Lsprio_2
	s_setprio 1

; #define PG8_STAGE(bufoff, gbase, voff) do { _Pragma("unroll") for (int _i = 0; _i < 2; ++_i) \
;         __builtin_amdgcn_global_load_lds((const unsigned*)((const char*)(gbase) + (voff)[_i]), (LAS unsigned*)(lds + (bufoff) + ldsw + _i * 8192), 16, 0, 0); } while (0)
; #define PG8_WAIT_V(n) asm volatile("s_waitcnt vmcnt(" #n ")" ::: "memory")
; #define PG8_BAR __builtin_amdgcn_s_barrier()
; template <class Epi, class Ptrs>
; __device__ __forceinline__ void gemm_phase(LAS unsigned char* lds, const int K, const StaticOrder& S, const Ptrs& P, const Epi& E) {
;     ...
;     for (int i = 0; i < 2; ++i) { int R, C; stage_rc(tid * 16 + i * 8192, R, C); const int Rb = (R & ~31) + perm32(R & 31);
;         voffA[i] = (unsigned)(R * K + C) * 2u; voffB[i] = (unsigned)(Rb * K + C) * 2u; }
;     const size_t kstep = (size_t)(BK * 2);
;     const size_t hstep = (size_t)HALF * K * 2;
;     const unsigned ldsw = (unsigned)wid * 1024u;
;     const int aoff = lds_byte(wr * 64 + fr, fq * 8), boff = lds_byte(wc * 32 + fr, fq * 8);
;     ...
;     Unit cur, nxt; int ui = 0;
;     if (!S.next(0, cur)) return;
;     f32x4 acc[2][2][4][2];
; #pragma unroll
;     for (int a = 0; a < 2; ++a)
; #pragma unroll
;         for (int b = 0; b < 2; ++b)
; #pragma unroll
;             for (int m = 0; m < 4; ++m)
; #pragma unroll
;                 for (int n = 0; n < 2; ++n) acc[a][b][m][n] = (f32x4){0.f, 0.f, 0.f, 0.f};
;     bf16x8 At[4][2], B0[2][2], B1[2][2];
;     const char* cA; const char* cB; P.get(cur, cA, cB);
;     PG8_STAGE(PG8_SB(0, 0), cB, voffB); PG8_STAGE(PG8_SA(0, 0), cA, voffA); PG8_STAGE(PG8_SB(0, 1), cB + hstep, voffB); PG8_STAGE(PG8_SA(0, 1), cA + hstep, voffA);
;     if (wr == 1) PG8_BAR;
;     PG8_WAIT_V(4); PG8_BAR;
;     PG8_STAGE(PG8_SB(1, 0), cB + kstep, voffB); PG8_STAGE(PG8_SA(1, 0), cA + kstep, voffA); PG8_STAGE(PG8_SB(1, 1), cB + hstep + kstep, voffB);
;     PG8_WAIT_V(6); PG8_BAR;
;     __device__ __forceinline__ void operator()(const f32x4 (&acc)[2][2][4][2], const Unit& u, int ui, int wr, int wc, int fr, int fq) const {
;     ...
;                 const float r2 = tab[ui * 256 + rl];
.LBB0_516:
	s_lshl_b32 s1, s1, 5
	s_and_b32 s1, s1, 0x60
	s_lshl_b32 s10, s0, 13
	s_lshl_b32 s11, s1, 7
	s_add_u32 s6, s28, 0x2000000
	s_mov_b64 s[8:9], 0x80
	s_addc_u32 s7, s29, 0
	s_add_i32 m0, s17, 0x18000
	v_lshl_add_u64 v[6:7], v[6:7], 0, s[8:9]
	s_waitcnt vmcnt(4)
	s_barrier
	global_load_lds_dwordx4 v[6:7], off
	v_lshl_add_u64 v[4:5], v[4:5], 0, s[8:9]
	s_add_i32 m0, s17, 0x1a000
	s_add_i32 s28, s17, 0x8000
	s_add_i32 s29, s17, 0xa000
	global_load_lds_dwordx4 v[4:5], off
	v_lshl_add_u64 v[2:3], v[2:3], 0, s[8:9]
	s_mov_b32 m0, s28
	s_add_u32 s4, s22, 0x100080
	global_load_lds_dwordx4 v[2:3], off
	v_lshl_add_u64 v[0:1], v[0:1], 0, s[8:9]
	s_mov_b32 m0, s29
	s_addc_u32 s5, s23, 0
	global_load_lds_dwordx4 v[0:1], off
	s_add_i32 m0, s17, 0x1c000
	v_lshl_add_u64 v[0:1], s[4:5], 0, v[162:163]
	global_load_lds_dwordx4 v[0:1], off
	v_lshl_add_u64 v[0:1], s[4:5], 0, v[166:167]
	s_add_i32 m0, s17, 0x1e000
	v_lshlrev_b32_e32 v2, 6, v208
	global_load_lds_dwordx4 v[0:1], off
	v_and_b32_e32 v0, 15, v208
	v_lshlrev_b32_e32 v1, 1, v11
	s_movk_i32 s4, 0x3c0
	v_lshl_or_b32 v186, s0, 6, v0
	v_and_or_b32 v2, v2, s4, v1
	v_lshlrev_b32_e32 v3, 2, v208
	v_lshl_or_b32 v0, v0, 6, v1
	v_lshlrev_b32_e32 v1, 2, v186
	s_add_i32 s0, 0, 0x20000
	v_and_b32_e32 v3, 32, v3
	v_and_b32_e32 v4, 32, v1
	v_add_u32_e32 v192, s0, v1
	v_lshlrev_b32_e32 v1, 10, v208
	v_bitop3_b32 v187, s11, v2, v3 bitop3:0xf6
	v_and_b32_e32 v1, 0xe0000, v1
	v_lshlrev_b32_e32 v2, 13, v10
	v_or3_b32 v1, v8, v1, v2
	v_add_u32_e32 v168, v1, v9
	v_lshlrev_b32_e32 v1, 6, v12
	s_waitcnt vmcnt(6)
	v_and_b32_e32 v1, 0x1e0000, v1
	v_bitop3_b32 v0, v0, s10, v4 bitop3:0xde
	v_or3_b32 v1, v8, v1, v2
	s_add_i32 s42, 0, 0x10000
	s_add_i32 s43, 0, 0x14000
	v_or_b32_e32 v188, 16, v186
	v_or_b32_e32 v189, 32, v186
	v_or_b32_e32 v190, 48, v186
	v_or_b32_e32 v191, s1, v11
	v_mov_b32_e32 v169, v163
	v_add_u32_e32 v170, v1, v9
	v_mov_b32_e32 v171, v163
	v_mov_b64_e32 v[172:173], 0x600
	v_mov_b64_e32 v[174:175], 0x5ff
	v_add_u32_e32 v193, s42, v187
	v_add_u32_e32 v194, 0, v0
	v_add_u32_e32 v195, s43, v187
	s_cmpk_gt_u32 s33, 0xff
	s_cbranch_scc1 .Lsprio_3
	s_setprio 1
